# deleted the adjacent s_setprio 0 / s_setprio 1 pairs in the middle of each 32-MFMA block of the K-loop
# speedup vs baseline: 1.0094x; 1.0080x over previous
; #define PG8_STAGE(bufoff, gbase, voff) do { _Pragma("unroll") for (int _i = 0; _i < 2; ++_i) \
;         __builtin_amdgcn_global_load_lds((const unsigned*)((const char*)(gbase) + (voff)[_i]), (PG8_LAS unsigned*)(lds + (bufoff) + ldsw + _i * 8192), 16, 0, 0); } while (0)
; #define PG8_LDA(dst, b, h) do { _Pragma("unroll") for (int m = 0; m < 4; ++m) _Pragma("unroll") for (int k = 0; k < 2; ++k) dst[m][k] = *(const PG8_LAS bf16x8*)(lds + PG8_SA(b, h) + aoff + m * 2048 + k * 1024); } while (0)
; #define PG8_LDB(dst, b, h) do { _Pragma("unroll") for (int n = 0; n < 2; ++n) _Pragma("unroll") for (int k = 0; k < 2; ++k) dst[n][k] = *(const PG8_LAS bf16x8*)(lds + PG8_SB(b, h) + boff + n * 2048 + k * 1024); } while (0)
; #define PG8_MMA(ai, bj, At, Bt) do { __builtin_amdgcn_s_setprio(1); _Pragma("unroll") for (int m = 0; m < 4; ++m) _Pragma("unroll") for (int n = 0; n < 2; ++n) _Pragma("unroll") for (int k = 0; k < 2; ++k) \
;         acc[ai][bj][m][n] = __builtin_amdgcn_mfma_f32_16x16x32_bf16(Bt[n][k], At[m][k], acc[ai][bj][m][n], 0, 0, 0); __builtin_amdgcn_s_setprio(0); } while (0)
; #define PG8_WAIT_V(n) asm volatile("s_waitcnt vmcnt(" #n ")" ::: "memory")
; #define PG8_WAIT_L(n) asm volatile("s_waitcnt lgkmcnt(" #n ")" ::: "memory")
; #define PG8_BAR __builtin_amdgcn_s_barrier()
; #define PG8_SCHED __builtin_amdgcn_sched_barrier(0)
; template <class Epi, class Sched, bool ALIGN_EPI = false, bool SP2 = false>
; __device__ __forceinline__ void gemm_phase(PG8_LAS unsigned char* lds, const Gemm g, const Sched& S, const Epi& E) {
;     ...
;             const bool last = (t == nt - 2);
;             const char* a1 = cA + (size_t)(t + 1) * kstep;
;             const char* a2 = last ? nA : cA + (size_t)(t + 2) * kstep; const char* b2 = last ? nB : cB + (size_t)(t + 2) * kstep;
;             const char* a3 = a2 + kstep; const char* b3 = b2 + kstep;
;             if (last && has_next) S.a_ready(nxt);
;             if constexpr (SP2) {
;             PG8_LDB(B0, 0, 0); PG8_LDB(B1, 0, 1); PG8_SCHED; PG8_LDA(At, 0, 0); PG8_STAGE(PG8_SA(1, 1), a1 + hstep, voffA);
;             PG8_WAIT_V(8); PG8_WAIT_L(0); PG8_BAR; PG8_MMA(0, 0, At, B0); PG8_MMA(0, 1, At, B1); PG8_BAR; PG8_SCHED;
;             PG8_LDA(At, 0, 1); PG8_STAGE(PG8_SB(0, 0), b2, voffB); PG8_STAGE(PG8_SB(0, 1), b2 + hstep, voffB); PG8_STAGE(PG8_SA(0, 0), a2, voffA);
.LBB0_441:
	s_add_i32 s61, s44, 2
	s_add_u32 s64, s42, 0x80
	s_addc_u32 s45, s43, 0
	s_add_i32 s66, 0, 0x10000
	s_cmp_eq_u32 s99, s44
	s_cselect_b32 s45, s29, s45
	s_cselect_b32 s44, s28, s64
	s_cselect_b32 s65, s21, s60
	s_cselect_b32 s64, s20, s17
	s_add_i32 s67, 0, 0x14000
	v_add_u32_e32 v142, s66, v228
	v_add_u32_e32 v158, s67, v228
	ds_read_b128 v[130:133], v142
	ds_read_b128 v[134:137], v142 offset:1024
	ds_read_b128 v[138:141], v142 offset:2048
	ds_read_b128 v[142:145], v142 offset:3072
	ds_read_b128 v[146:149], v158
	ds_read_b128 v[150:153], v158 offset:1024
	ds_read_b128 v[154:157], v158 offset:2048
	ds_read_b128 v[158:161], v158 offset:3072
	v_lshl_add_u64 v[206:207], s[42:43], 0, v[190:191]
	s_add_i32 m0, s93, 0xc000
	ds_read_b128 v[162:165], v230
	ds_read_b128 v[166:169], v230 offset:1024
	ds_read_b128 v[170:173], v230 offset:2048
	ds_read_b128 v[174:177], v230 offset:3072
	ds_read_b128 v[178:181], v230 offset:4096
	ds_read_b128 v[194:197], v230 offset:5120
	ds_read_b128 v[198:201], v230 offset:6144
	ds_read_b128 v[202:205], v230 offset:7168
	global_load_lds_dwordx4 v[206:207], off
	v_lshl_add_u64 v[206:207], s[42:43], 0, v[192:193]
	s_add_i32 m0, s93, 0xe000
	s_nop 0
	global_load_lds_dwordx4 v[206:207], off
	s_waitcnt vmcnt(8) lgkmcnt(0)
	s_barrier
	s_setprio 1
	v_mfma_f32_16x16x32_bf16 v[126:129], v[130:133], v[162:165], v[126:129]
	v_mfma_f32_16x16x32_bf16 v[122:125], v[138:141], v[162:165], v[122:125]
	v_mfma_f32_16x16x32_bf16 v[110:113], v[130:133], v[170:173], v[110:113]
	v_mfma_f32_16x16x32_bf16 v[102:105], v[138:141], v[170:173], v[102:105]
	v_mfma_f32_16x16x32_bf16 v[94:97], v[130:133], v[178:181], v[94:97]
	v_mfma_f32_16x16x32_bf16 v[86:89], v[138:141], v[178:181], v[86:89]
	v_mfma_f32_16x16x32_bf16 v[78:81], v[130:133], v[198:201], v[78:81]
	v_mfma_f32_16x16x32_bf16 v[70:73], v[138:141], v[198:201], v[70:73]
	v_mfma_f32_16x16x32_bf16 v[126:129], v[134:137], v[166:169], v[126:129]
	v_mfma_f32_16x16x32_bf16 v[122:125], v[142:145], v[166:169], v[122:125]
	v_mfma_f32_16x16x32_bf16 v[110:113], v[134:137], v[174:177], v[110:113]
	v_mfma_f32_16x16x32_bf16 v[102:105], v[142:145], v[174:177], v[102:105]
	v_mfma_f32_16x16x32_bf16 v[94:97], v[134:137], v[194:197], v[94:97]
	v_mfma_f32_16x16x32_bf16 v[86:89], v[142:145], v[194:197], v[86:89]
	v_mfma_f32_16x16x32_bf16 v[78:81], v[134:137], v[202:205], v[78:81]
	v_mfma_f32_16x16x32_bf16 v[70:73], v[142:145], v[202:205], v[70:73]
	v_mfma_f32_16x16x32_bf16 v[118:121], v[146:149], v[162:165], v[118:121]
	v_mfma_f32_16x16x32_bf16 v[114:117], v[154:157], v[162:165], v[114:117]
	v_mfma_f32_16x16x32_bf16 v[106:109], v[146:149], v[170:173], v[106:109]
	v_mfma_f32_16x16x32_bf16 v[98:101], v[154:157], v[170:173], v[98:101]
	v_mfma_f32_16x16x32_bf16 v[90:93], v[146:149], v[178:181], v[90:93]
	v_mfma_f32_16x16x32_bf16 v[82:85], v[154:157], v[178:181], v[82:85]
	v_mfma_f32_16x16x32_bf16 v[74:77], v[146:149], v[198:201], v[74:77]
	v_mfma_f32_16x16x32_bf16 v[66:69], v[154:157], v[198:201], v[66:69]
	v_mfma_f32_16x16x32_bf16 v[118:121], v[150:153], v[166:169], v[118:121]
	v_mfma_f32_16x16x32_bf16 v[114:117], v[158:161], v[166:169], v[114:117]
	v_mfma_f32_16x16x32_bf16 v[106:109], v[150:153], v[174:177], v[106:109]
	v_mfma_f32_16x16x32_bf16 v[98:101], v[158:161], v[174:177], v[98:101]
	v_mfma_f32_16x16x32_bf16 v[90:93], v[150:153], v[194:197], v[90:93]
	v_mfma_f32_16x16x32_bf16 v[82:85], v[158:161], v[194:197], v[82:85]
	v_mfma_f32_16x16x32_bf16 v[74:77], v[150:153], v[202:205], v[74:77]
	v_mfma_f32_16x16x32_bf16 v[66:69], v[158:161], v[202:205], v[66:69]
	s_setprio 0
	s_barrier
	s_add_i32 s66, s66, s92
	v_lshl_add_u64 v[206:207], s[64:65], 0, v[184:185]
	s_mov_b32 m0, s66
	ds_read_b128 v[162:165], v230 offset:16384
	ds_read_b128 v[166:169], v230 offset:17408
	ds_read_b128 v[170:173], v230 offset:18432
	ds_read_b128 v[174:177], v230 offset:19456
	ds_read_b128 v[178:181], v230 offset:20480
	ds_read_b128 v[194:197], v230 offset:21504
	ds_read_b128 v[198:201], v230 offset:22528
	ds_read_b128 v[202:205], v230 offset:23552
	global_load_lds_dwordx4 v[206:207], off
	s_add_i32 m0, s66, 0x2000
	v_lshl_add_u64 v[208:209], s[64:65], 0, v[188:189]
	s_add_u32 s64, s64, s26
	s_addc_u32 s65, s65, 0
	s_add_i32 s66, s67, s92
	global_load_lds_dwordx4 v[208:209], off
	v_lshl_add_u64 v[210:211], s[64:65], 0, v[184:185]
	s_mov_b32 m0, s66
	v_lshl_add_u64 v[232:233], s[64:65], 0, v[188:189]
	global_load_lds_dwordx4 v[210:211], off
	s_add_i32 m0, s66, 0x2000
	v_lshl_add_u64 v[234:235], s[44:45], 0, v[182:183]
	global_load_lds_dwordx4 v[232:233], off
	s_mov_b32 m0, s93
	v_lshl_add_u64 v[236:237], s[44:45], 0, v[186:187]
	global_load_lds_dwordx4 v[234:235], off
	s_mov_b32 m0, s94
	s_nop 0
	global_load_lds_dwordx4 v[236:237], off
	s_waitcnt vmcnt(8) lgkmcnt(0)
	s_barrier
; #define PG8_STAGE(bufoff, gbase, voff) do { _Pragma("unroll") for (int _i = 0; _i < 2; ++_i) \
;         __builtin_amdgcn_global_load_lds((const unsigned*)((const char*)(gbase) + (voff)[_i]), (PG8_LAS unsigned*)(lds + (bufoff) + ldsw + _i * 8192), 16, 0, 0); } while (0)
; #define PG8_LDA(dst, b, h) do { _Pragma("unroll") for (int m = 0; m < 4; ++m) _Pragma("unroll") for (int k = 0; k < 2; ++k) dst[m][k] = *(const PG8_LAS bf16x8*)(lds + PG8_SA(b, h) + aoff + m * 2048 + k * 1024); } while (0)
; #define PG8_LDB(dst, b, h) do { _Pragma("unroll") for (int n = 0; n < 2; ++n) _Pragma("unroll") for (int k = 0; k < 2; ++k) dst[n][k] = *(const PG8_LAS bf16x8*)(lds + PG8_SB(b, h) + boff + n * 2048 + k * 1024); } while (0)
; #define PG8_MMA(ai, bj, At, Bt) do { __builtin_amdgcn_s_setprio(1); _Pragma("unroll") for (int m = 0; m < 4; ++m) _Pragma("unroll") for (int n = 0; n < 2; ++n) _Pragma("unroll") for (int k = 0; k < 2; ++k) \
;         acc[ai][bj][m][n] = __builtin_amdgcn_mfma_f32_16x16x32_bf16(Bt[n][k], At[m][k], acc[ai][bj][m][n], 0, 0, 0); __builtin_amdgcn_s_setprio(0); } while (0)
; #define PG8_WAIT_V(n) asm volatile("s_waitcnt vmcnt(" #n ")" ::: "memory")
; #define PG8_WAIT_L(n) asm volatile("s_waitcnt lgkmcnt(" #n ")" ::: "memory")
; #define PG8_BAR __builtin_amdgcn_s_barrier()
; #define PG8_SCHED __builtin_amdgcn_sched_barrier(0)
; template <class Epi, class Sched, bool ALIGN_EPI = false, bool SP2 = false>
; __device__ __forceinline__ void gemm_phase(PG8_LAS unsigned char* lds, const Gemm g, const Sched& S, const Epi& E) {
;     ...
;             PG8_WAIT_V(8); PG8_WAIT_L(0); PG8_BAR; PG8_MMA(1, 0, At, B0); PG8_MMA(1, 1, At, B1); PG8_BAR; PG8_SCHED;
;             PG8_LDB(B0, 1, 0); PG8_LDB(B1, 1, 1); PG8_SCHED; PG8_LDA(At, 1, 0); PG8_STAGE(PG8_SA(0, 1), a2 + hstep, voffA);
;             PG8_WAIT_V(8); PG8_WAIT_L(0); PG8_BAR; PG8_MMA(0, 0, At, B0); PG8_MMA(0, 1, At, B1); PG8_BAR; PG8_SCHED;
	s_setprio 1
	v_mfma_f32_16x16x32_bf16 v[62:65], v[130:133], v[162:165], v[62:65]
	v_mfma_f32_16x16x32_bf16 v[54:57], v[138:141], v[162:165], v[54:57]
	v_mfma_f32_16x16x32_bf16 v[46:49], v[130:133], v[170:173], v[46:49]
	v_mfma_f32_16x16x32_bf16 v[38:41], v[138:141], v[170:173], v[38:41]
	v_mfma_f32_16x16x32_bf16 v[30:33], v[130:133], v[178:181], v[30:33]
	v_mfma_f32_16x16x32_bf16 v[22:25], v[138:141], v[178:181], v[22:25]
	v_mfma_f32_16x16x32_bf16 v[14:17], v[130:133], v[198:201], v[14:17]
	v_mfma_f32_16x16x32_bf16 v[6:9], v[138:141], v[198:201], v[6:9]
	v_mfma_f32_16x16x32_bf16 v[62:65], v[134:137], v[166:169], v[62:65]
	v_mfma_f32_16x16x32_bf16 v[54:57], v[142:145], v[166:169], v[54:57]
	v_mfma_f32_16x16x32_bf16 v[46:49], v[134:137], v[174:177], v[46:49]
	v_mfma_f32_16x16x32_bf16 v[38:41], v[142:145], v[174:177], v[38:41]
	v_mfma_f32_16x16x32_bf16 v[30:33], v[134:137], v[194:197], v[30:33]
	v_mfma_f32_16x16x32_bf16 v[22:25], v[142:145], v[194:197], v[22:25]
	v_mfma_f32_16x16x32_bf16 v[14:17], v[134:137], v[202:205], v[14:17]
	v_mfma_f32_16x16x32_bf16 v[6:9], v[142:145], v[202:205], v[6:9]
	v_mfma_f32_16x16x32_bf16 v[58:61], v[146:149], v[162:165], v[58:61]
	v_mfma_f32_16x16x32_bf16 v[50:53], v[154:157], v[162:165], v[50:53]
	v_mfma_f32_16x16x32_bf16 v[42:45], v[146:149], v[170:173], v[42:45]
	v_mfma_f32_16x16x32_bf16 v[34:37], v[154:157], v[170:173], v[34:37]
	v_mfma_f32_16x16x32_bf16 v[26:29], v[146:149], v[178:181], v[26:29]
	v_mfma_f32_16x16x32_bf16 v[18:21], v[154:157], v[178:181], v[18:21]
	v_mfma_f32_16x16x32_bf16 v[10:13], v[146:149], v[198:201], v[10:13]
	v_mfma_f32_16x16x32_bf16 v[2:5], v[154:157], v[198:201], v[2:5]
	v_mfma_f32_16x16x32_bf16 v[58:61], v[150:153], v[166:169], v[58:61]
	v_mfma_f32_16x16x32_bf16 v[50:53], v[158:161], v[166:169], v[50:53]
	v_mfma_f32_16x16x32_bf16 v[42:45], v[150:153], v[174:177], v[42:45]
	v_mfma_f32_16x16x32_bf16 v[34:37], v[158:161], v[174:177], v[34:37]
	v_mfma_f32_16x16x32_bf16 v[26:29], v[150:153], v[194:197], v[26:29]
	v_mfma_f32_16x16x32_bf16 v[18:21], v[158:161], v[194:197], v[18:21]
	v_mfma_f32_16x16x32_bf16 v[10:13], v[150:153], v[202:205], v[10:13]
	v_mfma_f32_16x16x32_bf16 v[2:5], v[158:161], v[202:205], v[2:5]
	s_setprio 0
	s_barrier
	s_add_i32 s64, 0, 0x18000
	s_add_i32 s65, 0, 0x1c000
	v_add_u32_e32 v142, s64, v228
	v_add_u32_e32 v158, s65, v228
	ds_read_b128 v[130:133], v142
	ds_read_b128 v[134:137], v142 offset:1024
	ds_read_b128 v[138:141], v142 offset:2048
	ds_read_b128 v[142:145], v142 offset:3072
	ds_read_b128 v[146:149], v158
	ds_read_b128 v[150:153], v158 offset:1024
	ds_read_b128 v[154:157], v158 offset:2048
	ds_read_b128 v[158:161], v158 offset:3072
	s_add_u32 s44, s44, s26
	s_addc_u32 s45, s45, 0
	s_mov_b32 m0, s95
	v_lshl_add_u64 v[238:239], s[44:45], 0, v[182:183]
	ds_read_b128 v[162:165], v230 offset:32768
	ds_read_b128 v[166:169], v230 offset:33792
	ds_read_b128 v[170:173], v230 offset:34816
	ds_read_b128 v[174:177], v230 offset:35840
	ds_read_b128 v[178:181], v230 offset:36864
	ds_read_b128 v[194:197], v230 offset:37888
	ds_read_b128 v[198:201], v230 offset:38912
	ds_read_b128 v[202:205], v230 offset:39936
	global_load_lds_dwordx4 v[238:239], off
	v_lshl_add_u64 v[238:239], s[44:45], 0, v[186:187]
	s_mov_b32 m0, s96
	s_nop 0
	global_load_lds_dwordx4 v[238:239], off
	s_waitcnt vmcnt(8) lgkmcnt(0)
	s_barrier
	s_setprio 1
	v_mfma_f32_16x16x32_bf16 v[126:129], v[130:133], v[162:165], v[126:129]
	v_mfma_f32_16x16x32_bf16 v[122:125], v[138:141], v[162:165], v[122:125]
	v_mfma_f32_16x16x32_bf16 v[110:113], v[130:133], v[170:173], v[110:113]
	v_mfma_f32_16x16x32_bf16 v[102:105], v[138:141], v[170:173], v[102:105]
	v_mfma_f32_16x16x32_bf16 v[94:97], v[130:133], v[178:181], v[94:97]
	v_mfma_f32_16x16x32_bf16 v[86:89], v[138:141], v[178:181], v[86:89]
	v_mfma_f32_16x16x32_bf16 v[78:81], v[130:133], v[198:201], v[78:81]
	v_mfma_f32_16x16x32_bf16 v[70:73], v[138:141], v[198:201], v[70:73]
	v_mfma_f32_16x16x32_bf16 v[126:129], v[134:137], v[166:169], v[126:129]
	v_mfma_f32_16x16x32_bf16 v[122:125], v[142:145], v[166:169], v[122:125]
	v_mfma_f32_16x16x32_bf16 v[110:113], v[134:137], v[174:177], v[110:113]
	v_mfma_f32_16x16x32_bf16 v[102:105], v[142:145], v[174:177], v[102:105]
	v_mfma_f32_16x16x32_bf16 v[94:97], v[134:137], v[194:197], v[94:97]
	v_mfma_f32_16x16x32_bf16 v[86:89], v[142:145], v[194:197], v[86:89]
	v_mfma_f32_16x16x32_bf16 v[78:81], v[134:137], v[202:205], v[78:81]
	v_mfma_f32_16x16x32_bf16 v[70:73], v[142:145], v[202:205], v[70:73]
	v_mfma_f32_16x16x32_bf16 v[118:121], v[146:149], v[162:165], v[118:121]
	v_mfma_f32_16x16x32_bf16 v[114:117], v[154:157], v[162:165], v[114:117]
	v_mfma_f32_16x16x32_bf16 v[106:109], v[146:149], v[170:173], v[106:109]
	v_mfma_f32_16x16x32_bf16 v[98:101], v[154:157], v[170:173], v[98:101]
	v_mfma_f32_16x16x32_bf16 v[90:93], v[146:149], v[178:181], v[90:93]
	v_mfma_f32_16x16x32_bf16 v[82:85], v[154:157], v[178:181], v[82:85]
	v_mfma_f32_16x16x32_bf16 v[74:77], v[146:149], v[198:201], v[74:77]
	v_mfma_f32_16x16x32_bf16 v[66:69], v[154:157], v[198:201], v[66:69]
	v_mfma_f32_16x16x32_bf16 v[118:121], v[150:153], v[166:169], v[118:121]
	v_mfma_f32_16x16x32_bf16 v[114:117], v[158:161], v[166:169], v[114:117]
	v_mfma_f32_16x16x32_bf16 v[106:109], v[150:153], v[174:177], v[106:109]
	v_mfma_f32_16x16x32_bf16 v[98:101], v[158:161], v[174:177], v[98:101]
	v_mfma_f32_16x16x32_bf16 v[90:93], v[150:153], v[194:197], v[90:93]
	v_mfma_f32_16x16x32_bf16 v[82:85], v[158:161], v[194:197], v[82:85]
	v_mfma_f32_16x16x32_bf16 v[74:77], v[150:153], v[202:205], v[74:77]
	v_mfma_f32_16x16x32_bf16 v[66:69], v[158:161], v[202:205], v[66:69]
	s_setprio 0
	s_barrier
; #define PG8_STAGE(bufoff, gbase, voff) do { _Pragma("unroll") for (int _i = 0; _i < 2; ++_i) \
;         __builtin_amdgcn_global_load_lds((const unsigned*)((const char*)(gbase) + (voff)[_i]), (PG8_LAS unsigned*)(lds + (bufoff) + ldsw + _i * 8192), 16, 0, 0); } while (0)
; #define PG8_LDA(dst, b, h) do { _Pragma("unroll") for (int m = 0; m < 4; ++m) _Pragma("unroll") for (int k = 0; k < 2; ++k) dst[m][k] = *(const PG8_LAS bf16x8*)(lds + PG8_SA(b, h) + aoff + m * 2048 + k * 1024); } while (0)
; #define PG8_MMA(ai, bj, At, Bt) do { __builtin_amdgcn_s_setprio(1); _Pragma("unroll") for (int m = 0; m < 4; ++m) _Pragma("unroll") for (int n = 0; n < 2; ++n) _Pragma("unroll") for (int k = 0; k < 2; ++k) \
;         acc[ai][bj][m][n] = __builtin_amdgcn_mfma_f32_16x16x32_bf16(Bt[n][k], At[m][k], acc[ai][bj][m][n], 0, 0, 0); __builtin_amdgcn_s_setprio(0); } while (0)
; #define PG8_WAIT_V(n) asm volatile("s_waitcnt vmcnt(" #n ")" ::: "memory")
; #define PG8_WAIT_L(n) asm volatile("s_waitcnt lgkmcnt(" #n ")" ::: "memory")
; #define PG8_BAR __builtin_amdgcn_s_barrier()
; #define PG8_SCHED __builtin_amdgcn_sched_barrier(0)
; template <class Epi, class Sched, bool ALIGN_EPI = false, bool SP2 = false>
; __device__ __forceinline__ void gemm_phase(PG8_LAS unsigned char* lds, const Gemm g, const Sched& S, const Epi& E) {
;     ...
;             PG8_LDA(At, 1, 1); PG8_STAGE(PG8_SB(1, 0), b3, voffB); PG8_STAGE(PG8_SB(1, 1), b3 + hstep, voffB); PG8_STAGE(PG8_SA(1, 0), a3, voffA);
;             PG8_WAIT_V(8); PG8_WAIT_L(0); PG8_BAR; PG8_MMA(1, 0, At, B0); PG8_MMA(1, 1, At, B1); PG8_BAR; PG8_SCHED;
;     ...
;         if constexpr (ALIGN_EPI) { if (wr == 0) PG8_BAR; }
;         if constexpr (!Epi::AFTER_DRAIN) { E(acc, cur, wr, wc, fr, fq); S.done(cur); }
	s_add_i32 s44, s64, s92
	v_lshl_add_u64 v[206:207], v[206:207], 0, s[34:35]
	s_mov_b32 m0, s44
	ds_read_b128 v[162:165], v230 offset:49152
	ds_read_b128 v[166:169], v230 offset:50176
	ds_read_b128 v[170:173], v230 offset:51200
	ds_read_b128 v[174:177], v230 offset:52224
	ds_read_b128 v[178:181], v230 offset:53248
	ds_read_b128 v[194:197], v230 offset:54272
	ds_read_b128 v[198:201], v230 offset:55296
	ds_read_b128 v[202:205], v230 offset:56320
	global_load_lds_dwordx4 v[206:207], off
	v_lshl_add_u64 v[206:207], v[208:209], 0, s[34:35]
	s_add_i32 m0, s44, 0x2000
	s_add_i32 s44, s65, s92
	global_load_lds_dwordx4 v[206:207], off
	v_lshl_add_u64 v[206:207], v[210:211], 0, s[34:35]
	s_mov_b32 m0, s44
	s_nop 0
	global_load_lds_dwordx4 v[206:207], off
	v_lshl_add_u64 v[206:207], v[232:233], 0, s[34:35]
	s_add_i32 m0, s44, 0x2000
	s_nop 0
	global_load_lds_dwordx4 v[206:207], off
	v_lshl_add_u64 v[206:207], v[234:235], 0, s[34:35]
	s_mov_b32 m0, s97
	s_nop 0
	global_load_lds_dwordx4 v[206:207], off
	v_lshl_add_u64 v[206:207], v[236:237], 0, s[34:35]
	s_mov_b32 m0, s98
	s_nop 0
	global_load_lds_dwordx4 v[206:207], off
	s_waitcnt vmcnt(8) lgkmcnt(0)
	s_barrier
	s_setprio 1
	v_mfma_f32_16x16x32_bf16 v[62:65], v[130:133], v[162:165], v[62:65]
	v_mfma_f32_16x16x32_bf16 v[54:57], v[138:141], v[162:165], v[54:57]
	v_mfma_f32_16x16x32_bf16 v[46:49], v[130:133], v[170:173], v[46:49]
	v_mfma_f32_16x16x32_bf16 v[38:41], v[138:141], v[170:173], v[38:41]
	v_mfma_f32_16x16x32_bf16 v[30:33], v[130:133], v[178:181], v[30:33]
	v_mfma_f32_16x16x32_bf16 v[22:25], v[138:141], v[178:181], v[22:25]
	v_mfma_f32_16x16x32_bf16 v[14:17], v[130:133], v[198:201], v[14:17]
	v_mfma_f32_16x16x32_bf16 v[6:9], v[138:141], v[198:201], v[6:9]
	v_mfma_f32_16x16x32_bf16 v[62:65], v[134:137], v[166:169], v[62:65]
	v_mfma_f32_16x16x32_bf16 v[54:57], v[142:145], v[166:169], v[54:57]
	v_mfma_f32_16x16x32_bf16 v[46:49], v[134:137], v[174:177], v[46:49]
	v_mfma_f32_16x16x32_bf16 v[38:41], v[142:145], v[174:177], v[38:41]
	v_mfma_f32_16x16x32_bf16 v[30:33], v[134:137], v[194:197], v[30:33]
	v_mfma_f32_16x16x32_bf16 v[22:25], v[142:145], v[194:197], v[22:25]
	v_mfma_f32_16x16x32_bf16 v[14:17], v[134:137], v[202:205], v[14:17]
	v_mfma_f32_16x16x32_bf16 v[6:9], v[142:145], v[202:205], v[6:9]
	v_mfma_f32_16x16x32_bf16 v[58:61], v[146:149], v[162:165], v[58:61]
	v_mfma_f32_16x16x32_bf16 v[50:53], v[154:157], v[162:165], v[50:53]
	v_mfma_f32_16x16x32_bf16 v[42:45], v[146:149], v[170:173], v[42:45]
	v_mfma_f32_16x16x32_bf16 v[34:37], v[154:157], v[170:173], v[34:37]
	v_mfma_f32_16x16x32_bf16 v[26:29], v[146:149], v[178:181], v[26:29]
	v_mfma_f32_16x16x32_bf16 v[18:21], v[154:157], v[178:181], v[18:21]
	v_mfma_f32_16x16x32_bf16 v[10:13], v[146:149], v[198:201], v[10:13]
	v_mfma_f32_16x16x32_bf16 v[2:5], v[154:157], v[198:201], v[2:5]
	v_mfma_f32_16x16x32_bf16 v[58:61], v[150:153], v[166:169], v[58:61]
	v_mfma_f32_16x16x32_bf16 v[50:53], v[158:161], v[166:169], v[50:53]
	v_mfma_f32_16x16x32_bf16 v[42:45], v[150:153], v[174:177], v[42:45]
	v_mfma_f32_16x16x32_bf16 v[34:37], v[158:161], v[174:177], v[34:37]
	v_mfma_f32_16x16x32_bf16 v[26:29], v[150:153], v[194:197], v[26:29]
	v_mfma_f32_16x16x32_bf16 v[18:21], v[158:161], v[194:197], v[18:21]
	v_mfma_f32_16x16x32_bf16 v[10:13], v[150:153], v[202:205], v[10:13]
	v_mfma_f32_16x16x32_bf16 v[2:5], v[158:161], v[202:205], v[2:5]
	s_setprio 0
	s_barrier
	s_add_u32 s42, s42, 0x100
	s_addc_u32 s43, s43, 0
	s_add_u32 s17, s17, 0x100
	s_addc_u32 s60, s60, 0
	s_cmp_ge_u32 s61, s4
	s_mov_b32 s44, s61
	s_cbranch_scc0 .LBB0_441
	s_and_b64 vcc, exec, s[36:37]
	s_cbranch_vccz .LBB0_445
	s_barrier
	s_cmp_lt_i32 s0, 2
	s_mov_b64 s[42:43], -1
	s_cbranch_scc0 .LBB0_446
